# weight-conversion split: 12872 items in the prologue
# baseline (speedup 1.0000x reference)
; #define LAS __attribute__((address_space(3)))
;     __device__ __forceinline__ bf16* Win_t() const { return (bf16*)(ws + WS_WIN); }
;     __device__ __forceinline__ bf16* Wout_t() const { return (bf16*)(ws + WS_WOUT); }
;     __device__ __forceinline__ bf16* Wgu_t() const { return (bf16*)((unsigned char*)out + OUT_WGU); }
; __device__ __forceinline__ P0Item p0_decode(Frame& F, int it, int n4) {
;     constexpr int I_IN = (D / 64) * (NP1 / 64), I_OUT = (D / 64) * (D / 64), I_GU = (D / 64) * (2 * FF / 64);
;     P0Item q; int r = it;
;     if (r < I_IN) { const int nblk = NP1 / 64, kb = r / nblk, nb = r % nblk, n = nb * 64 + n4;
;         const int sc = n < SRC_GLR ? n : n + GRANK;
;         q.srcp = F.w_in + sc; q.ldw = DIN; q.kscale = F.norm1_w; q.K = D; q.WT = F.Win_t(); q.n0 = nb * 64; q.k0 = kb * 64; return q; }
;     r -= I_IN;
;     if (r < I_OUT) { const int nblk = D / 64, kb = r / nblk, nb = r % nblk;
;         q.srcp = F.w_out + nb * 64 + n4; q.ldw = D; q.kscale = nullptr; q.K = D; q.WT = F.Wout_t(); q.n0 = nb * 64; q.k0 = kb * 64; return q; }
;     r -= I_OUT;
;     if (r < I_GU) { const int nblk = 2 * FF / 64, kb = r / nblk, nb = r % nblk, n0 = nb * 64, pn = n0 >> 8, wc = (n0 >> 6) & 3, bj = n4 >> 5, hl = 32 * wc + (n4 & 31);
;         q.srcp = (bj ? F.w_up : F.w_gate) + pn * 128 + hl; q.ldw = FF; q.kscale = F.norm2_w; q.K = D; q.WT = F.Wgu_t(); q.n0 = n0; q.k0 = kb * 64; return q; }
; template <bool NT> __device__ __forceinline__ void p0_items(Frame& F, int it0, int it1, int gw, int nw) {
;     LAS unsigned char* scr = F.lds + F.wave * 16384;
;     const int n4 = (F.lane & 15) * 4, kr = F.lane >> 4;
;     f32x4 va[16], vb[16]; P0Item A, B; int it = it0 + gw;
;     if (it < it1) { A = p0_decode(F, it, n4); p0_load(A, kr, va); }
.LBB0_16:
	s_add_u32 s4, s54, 0x4000000
	s_addc_u32 s5, s55, 0
	v_lshlrev_b32_e32 v2, 2, v183
	s_add_u32 s6, s56, 0xa00000
	v_and_b32_e32 v141, 60, v2
	s_addc_u32 s7, s57, 0
	s_add_u32 s18, s56, 0x2800000
	v_and_b32_e32 v142, 28, v2
	v_mov_b32_e32 v2, s93
	v_mov_b32_e32 v3, s91
	v_cmp_gt_u32_e32 vcc, 32, v141
	v_lshrrev_b32_e32 v1, 4, v183
	s_addc_u32 s19, s57, 0
	v_cndmask_b32_e32 v135, v2, v3, vcc
	v_mov_b32_e32 v2, s92
	v_mov_b32_e32 v3, s90
	s_cmpk_gt_i32 s16, 0x3247
	v_cndmask_b32_e32 v134, v2, v3, vcc
	v_or_b32_e32 v143, 4, v1
	v_or_b32_e32 v145, 8, v1
	v_or_b32_e32 v146, 12, v1
	v_or_b32_e32 v147, 16, v1
	v_or_b32_e32 v148, 20, v1
	v_or_b32_e32 v149, 24, v1
	v_or_b32_e32 v150, 28, v1
	v_or_b32_e32 v151, 32, v1
	v_or_b32_e32 v152, 36, v1
	v_or_b32_e32 v153, 40, v1
	v_or_b32_e32 v154, 44, v1
	v_or_b32_e32 v155, 48, v1
	v_or_b32_e32 v156, 52, v1
	v_or_b32_e32 v157, 56, v1
	v_or_b32_e32 v158, 60, v1
	s_cbranch_scc1 .LBB0_19
	s_mul_hi_i32 s1, s16, 0x51eb851f
	s_lshr_b32 s8, s1, 31
	s_ashr_i32 s1, s1, 6
	s_add_i32 s1, s1, s8
	s_mul_i32 s8, s1, 0xc8
	s_sub_i32 s8, s16, s8
	s_lshl_b32 s17, s8, 6
	v_or_b32_e32 v2, s17, v141
	s_movk_i32 s8, 0x1a00
	s_cmpk_lt_i32 s16, 0x1900
	v_cmp_gt_i32_e32 vcc, s8, v2
	s_cbranch_scc1 .LBB0_20
	s_cmpk_lt_u32 s16, 0x1d00
	s_cselect_b64 vcc, -1, 0
	s_add_i32 s1, s16, 0xe300
	s_and_b32 s8, s1, 0xffff
	s_mul_i32 s8, s8, 0xba2f
	s_lshr_b32 s8, s8, 23
	s_mul_i32 s9, s8, 0xb0
	s_sub_i32 s1, s1, s9
	s_and_b32 s1, s1, 0xffff
	s_lshl_b32 s10, s1, 5
	s_and_b32 s10, s10, 0x60
	s_lshl_b32 s9, s1, 6
	v_or_b32_e32 v4, s10, v142
	s_lshl_b32 s1, s1, 7
	s_and_b32 s10, s0, 0x7c0
	s_and_b32 s20, s1, 0x7e00
	s_mov_b32 s21, 0
	s_lshl_b32 s8, s8, 6
	s_lshl_b32 s0, s10, 2
	v_lshl_add_u64 v[2:3], v[134:135], 0, s[20:21]
	v_lshlrev_b32_e32 v4, 2, v4
	v_mov_b32_e32 v5, 0
	s_add_u32 s0, s50, s0
	v_lshl_add_u64 v[2:3], v[2:3], 0, v[4:5]
	s_addc_u32 s1, s51, 0
	v_lshlrev_b32_e32 v4, 2, v141
	v_lshl_add_u64 v[4:5], s[0:1], 0, v[4:5]
	s_lshl_b32 s0, s16, 1
	s_and_b32 s0, s0, 0x3fc0
	s_add_i32 s11, s0, 0xffffce00
	s_and_b64 s[0:1], vcc, exec
	s_movk_i32 s0, 0x800
	v_cndmask_b32_e32 v27, v3, v5, vcc
	v_cndmask_b32_e32 v26, v2, v4, vcc
	s_cselect_b32 s23, 0, s89
	s_cselect_b32 s22, 0, s88
	s_cselect_b32 s25, s7, s5
	s_cselect_b32 s24, s6, s4
	s_cselect_b32 s20, s0, 0x1600
	s_cselect_b32 s17, s10, s9
	s_cselect_b32 s63, s11, s8
	s_branch .LBB0_21

;     __device__ __forceinline__ bf16* Win_t() const { return (bf16*)(ws + WS_WIN); }
;     __device__ __forceinline__ bf16* Wout_t() const { return (bf16*)(ws + WS_WOUT); }
;     __device__ __forceinline__ bf16* Wgu_t() const { return (bf16*)((unsigned char*)out + OUT_WGU); }
; __device__ __forceinline__ P0Item p0_decode(Frame& F, int it, int n4) {
;     ...
;     if (r < I_IN) { const int nblk = NP1 / 64, kb = r / nblk, nb = r % nblk, n = nb * 64 + n4;
;         const int sc = n < SRC_GLR ? n : n + GRANK;
;         q.srcp = F.w_in + sc; q.ldw = DIN; q.kscale = F.norm1_w; q.K = D; q.WT = F.Win_t(); q.n0 = nb * 64; q.k0 = kb * 64; return q; }
;     r -= I_IN;
;     if (r < I_OUT) { const int nblk = D / 64, kb = r / nblk, nb = r % nblk;
;         q.srcp = F.w_out + nb * 64 + n4; q.ldw = D; q.kscale = nullptr; q.K = D; q.WT = F.Wout_t(); q.n0 = nb * 64; q.k0 = kb * 64; return q; }
;     r -= I_OUT;
;     if (r < I_GU) { const int nblk = 2 * FF / 64, kb = r / nblk, nb = r % nblk, n0 = nb * 64, pn = n0 >> 8, wc = (n0 >> 6) & 3, bj = n4 >> 5, hl = 32 * wc + (n4 & 31);
;         q.srcp = (bj ? F.w_up : F.w_gate) + pn * 128 + hl; q.ldw = FF; q.kscale = F.norm2_w; q.K = D; q.WT = F.Wgu_t(); q.n0 = n0; q.k0 = kb * 64; return q; }
; template <bool NT> __device__ __forceinline__ void p0_items(Frame& F, int it0, int it1, int gw, int nw) {
;     ...
;     while (it < it1) {
;         int itn = it + nw;
;         if (itn < it1) { B = p0_decode(F, itn, n4); p0_load(B, kr, vb); }
;         p0_finish<NT>(A, va, scr, F.lane);
;         it = itn; if (it >= it1) break;
;         itn = it + nw;
;         if (itn < it1) { A = p0_decode(F, itn, n4); p0_load(A, kr, va); }
.LBB0_57:
	s_cmpk_gt_i32 s65, 0x3247
	s_mov_b64 s[34:35], -1
	s_cbranch_scc1 .LBB0_56
	s_add_i32 s65, s65, s20
	s_cmpk_lt_i32 s65, 0x3248
	s_cselect_b64 s[68:69], -1, 0
	s_cmpk_gt_i32 s65, 0x3247
	s_cselect_b64 s[34:35], -1, 0
	s_and_b64 vcc, exec, s[34:35]
	s_cbranch_vccnz .LBB0_100
	s_cmpk_gt_i32 s65, 0x18ff
	s_cbranch_scc0 .LBB0_62
	s_cmpk_gt_u32 s65, 0x1cff
	s_cbranch_scc0 .LBB0_63
	s_add_i32 s0, s65, 0xe300
	s_and_b32 s1, s0, 0xffff
	s_mul_i32 s1, s1, 0xba2f
	s_lshr_b32 s1, s1, 23
	s_mul_i32 s8, s1, 0xb0
	s_sub_i32 s0, s0, s8
	s_and_b32 s0, s0, 0xffff
	s_lshl_b32 s8, s0, 5
	s_lshl_b32 s67, s0, 6
	s_and_b32 s8, s8, 0x60
	s_lshl_b32 s0, s0, 7
	v_or_b32_e32 v27, s8, v142
	s_and_b32 s26, s0, 0x7e00
	v_lshl_add_u64 v[28:29], v[134:135], 0, s[26:27]
	v_lshlrev_b32_e32 v46, 2, v27
	v_mov_b32_e32 v47, v26
	v_lshl_add_u64 v[138:139], v[28:29], 0, v[46:47]
	s_lshl_b32 s74, s1, 6
	s_mov_b64 s[28:29], s[88:89]
	s_mov_b64 s[70:71], 0x1600
	s_mov_b64 s[30:31], s[4:5]
	s_cbranch_execz .LBB0_64
	s_branch .LBB0_65

; #define GAS __attribute__((address_space(1)))
; #define LAS __attribute__((address_space(3)))
; __device__ __forceinline__ s16x4_t tr_read(LAS const unsigned char* p) { return __builtin_bit_cast(s16x4_t, __builtin_amdgcn_ds_read_tr16_b64_v4i16((LAS s16x4_t*)p)); }
; __device__ __forceinline__ bf16x8_t cat8(s16x4_t lo, s16x4_t hi) { return __builtin_shufflevector(lo, hi, 0, 1, 2, 3, 4, 5, 6, 7); }
; template <bool NT> __device__ __forceinline__ void p0_finish(const P0Item& q, f32x4 (&v)[16], LAS unsigned char* scr, int lane) {
;     ...
;         for (int i = 0; i < 16; ++i) v[i] = v[i] * q.kscale[q.k0 + 4 * i + kr];
;     }
; #pragma unroll
;     for (int i = 0; i < 16; ++i) { v2u w; w.x = cvtpk(v[i][0], v[i][1]); w.y = cvtpk(v[i][2], v[i][3]); *(LAS v2u*)(scr + (4 * i + kr) * RS + n4 * 2) = w; }
;     const int G = lane >> 4, i16 = lane & 15, qq = i16 >> 2, p = i16 & 3;
; #pragma unroll
;     for (int ng = 0; ng < 4; ++ng)
; #pragma unroll
;         for (int u = 0; u < 2; ++u) { const LAS unsigned char* rp = scr + (8 * (G + 4 * u) + qq) * RS + (16 * ng + 4 * p) * 2;
;             const bf16x8_t t = cat8(tr_read(rp), tr_read(rp + 4 * RS));
;             *(GAS bf16x8_t*)(q.WT + pg8::blk_off_b(q.n0 + 16 * ng + i16, q.k0 + 8 * (G + 4 * u), q.K)) = t; }
.LBB0_102:
	s_waitcnt vmcnt(0)
	v_cvt_pk_bf16_f32 v28, v2, v3
	v_cvt_pk_bf16_f32 v29, v4, v5
	v_cvt_pk_bf16_f32 v138, v6, v7
	v_cvt_pk_bf16_f32 v139, v8, v9
	ds_write2_b64 v165, v[28:29], v[138:139] offset1:72
	v_cvt_pk_bf16_f32 v28, v10, v11
	v_cvt_pk_bf16_f32 v29, v12, v13
	v_cvt_pk_bf16_f32 v138, v14, v15
	v_cvt_pk_bf16_f32 v139, v16, v17
	ds_write2_b64 v165, v[28:29], v[138:139] offset0:144 offset1:216
	v_cvt_pk_bf16_f32 v28, v18, v19
	v_cvt_pk_bf16_f32 v29, v20, v21
	v_cvt_pk_bf16_f32 v138, v22, v23
	v_cvt_pk_bf16_f32 v139, v24, v25
	v_add_u32_e32 v168, 0x800, v165
	ds_write2_b64 v168, v[28:29], v[138:139] offset0:32 offset1:104
	v_cvt_pk_bf16_f32 v28, v30, v31
	v_cvt_pk_bf16_f32 v29, v32, v33
	v_cvt_pk_bf16_f32 v138, v34, v35
	v_cvt_pk_bf16_f32 v139, v36, v37
	ds_write2_b64 v168, v[28:29], v[138:139] offset0:176 offset1:248
	v_cvt_pk_bf16_f32 v28, v38, v39
	v_cvt_pk_bf16_f32 v29, v40, v41
	v_cvt_pk_bf16_f32 v138, v42, v43
	v_cvt_pk_bf16_f32 v139, v44, v45
	v_add_u32_e32 v169, 0x1000, v165
	ds_write2_b64 v169, v[28:29], v[138:139] offset0:64 offset1:136
	v_cvt_pk_bf16_f32 v28, v50, v51
	v_cvt_pk_bf16_f32 v29, v52, v53
	v_cvt_pk_bf16_f32 v138, v58, v59
	v_cvt_pk_bf16_f32 v139, v60, v61
	v_add_u32_e32 v170, 0x1400, v165
	ds_write2_b64 v170, v[28:29], v[138:139] offset0:80 offset1:152
	v_cvt_pk_bf16_f32 v28, v74, v75
	v_cvt_pk_bf16_f32 v29, v76, v77
	v_cvt_pk_bf16_f32 v138, v82, v83
	v_cvt_pk_bf16_f32 v139, v84, v85
	v_add_u32_e32 v171, 0x1800, v165
	ds_write2_b64 v171, v[28:29], v[138:139] offset0:96 offset1:168
	v_cvt_pk_bf16_f32 v28, v94, v95
	v_cvt_pk_bf16_f32 v29, v96, v97
	v_cvt_pk_bf16_f32 v138, v102, v103
	v_cvt_pk_bf16_f32 v139, v104, v105
	v_add_u32_e32 v172, 0x1c00, v165
	v_add_u32_e32 v27, s17, v140
	ds_write2_b64 v172, v[28:29], v[138:139] offset0:112 offset1:184
	v_lshlrev_b32_e32 v28, 2, v27
	v_and_b32_e32 v28, 16, v28
	v_lshrrev_b32_e32 v29, 1, v27
	v_add_u32_e32 v138, s63, v160
	v_and_or_b32 v173, v29, s21, v28
	v_ashrrev_i32_e32 v28, 3, v27
	v_and_b32_e32 v139, 3, v27
	v_and_b32_e32 v182, 0xffffffe0, v28
	v_ashrrev_i32_e32 v204, 6, v138
	v_and_or_b32 v139, v29, 12, v139
	v_add_u32_e32 v28, v182, v204
	ds_read_b64_tr_b16 v[176:177], v166 offset:576
	v_ashrrev_i32_e32 v29, 31, v28
	v_lshlrev_b32_e32 v192, 5, v139
	v_and_b32_e32 v206, 31, v138
	v_and_b32_e32 v193, 16, v27
	v_lshrrev_b32_e32 v173, 3, v173
	v_bfe_u32 v205, v138, 5, 1
	v_bitop3_b32 v175, v192, v193, v206 bitop3:0x36
	v_lshlrev_b64 v[28:29], 15, v[28:29]
	v_lshlrev_b32_e32 v27, 9, v27
	v_or_b32_e32 v174, v173, v205
	v_lshl_add_u64 v[28:29], s[24:25], 0, v[28:29]
	v_and_b32_e32 v138, 0x4000, v27
	v_mov_b32_e32 v139, v26
	v_lshlrev_b32_e32 v27, 1, v175
	v_lshl_add_u64 v[28:29], v[28:29], 0, v[138:139]
	v_lshl_or_b32 v174, v174, 10, v27
	v_mov_b32_e32 v175, v26
	v_add_u32_e32 v27, s63, v161
	v_lshl_add_u64 v[28:29], v[28:29], 0, v[174:175]
	v_ashrrev_i32_e32 v207, 6, v27
	ds_read_b64_tr_b16 v[174:175], v166
	ds_read_b64_tr_b16 v[178:179], v166 offset:32
	ds_read_b64_tr_b16 v[184:185], v166 offset:64
	ds_read_b64_tr_b16 v[188:189], v166 offset:96
	ds_read_b64_tr_b16 v[180:181], v166 offset:608
	ds_read_b64_tr_b16 v[186:187], v166 offset:640
	ds_read_b64_tr_b16 v[190:191], v166 offset:672
	s_waitcnt lgkmcnt(6)
	global_store_dwordx4 v[28:29], v[174:177], off
	v_add_u32_e32 v28, v182, v207
	v_ashrrev_i32_e32 v29, 31, v28
	ds_read_b64_tr_b16 v[176:177], v167 offset:576
	v_bfe_u32 v182, v27, 5, 1
	v_and_b32_e32 v27, 31, v27
	v_lshlrev_b64 v[28:29], 15, v[28:29]
	v_bitop3_b32 v174, v192, v193, v27 bitop3:0x36
	v_lshl_add_u64 v[28:29], s[24:25], 0, v[28:29]
	v_or_b32_e32 v173, v173, v182
	v_lshl_add_u64 v[28:29], v[28:29], 0, v[138:139]
	v_lshlrev_b32_e32 v138, 1, v174
	v_lshl_or_b32 v138, v173, 10, v138
	v_lshl_add_u64 v[28:29], v[28:29], 0, v[138:139]
	v_add_u32_e32 v138, s17, v162
	ds_read_b64_tr_b16 v[174:175], v167
	ds_read_b64_tr_b16 v[192:193], v167 offset:32
	ds_read_b64_tr_b16 v[196:197], v167 offset:64
	ds_read_b64_tr_b16 v[200:201], v167 offset:96
	ds_read_b64_tr_b16 v[194:195], v167 offset:608
	ds_read_b64_tr_b16 v[198:199], v167 offset:640
	ds_read_b64_tr_b16 v[202:203], v167 offset:672
	s_waitcnt lgkmcnt(6)
; #define GAS __attribute__((address_space(1)))
; #define LAS __attribute__((address_space(3)))
; #define LDS_WAIT() asm volatile("s_waitcnt lgkmcnt(0)" ::: "memory")
; __device__ __forceinline__ s16x4_t tr_read(LAS const unsigned char* p) { return __builtin_bit_cast(s16x4_t, __builtin_amdgcn_ds_read_tr16_b64_v4i16((LAS s16x4_t*)p)); }
; __device__ __forceinline__ bf16x8_t cat8(s16x4_t lo, s16x4_t hi) { return __builtin_shufflevector(lo, hi, 0, 1, 2, 3, 4, 5, 6, 7); }
; template <bool NT> __device__ __forceinline__ void p0_finish(const P0Item& q, f32x4 (&v)[16], LAS unsigned char* scr, int lane) {
;     ...
;         for (int u = 0; u < 2; ++u) { const LAS unsigned char* rp = scr + (8 * (G + 4 * u) + qq) * RS + (16 * ng + 4 * p) * 2;
;             const bf16x8_t t = cat8(tr_read(rp), tr_read(rp + 4 * RS));
;             *(GAS bf16x8_t*)(q.WT + pg8::blk_off_b(q.n0 + 16 * ng + i16, q.k0 + 8 * (G + 4 * u), q.K)) = t; }
;     LDS_WAIT(); asm volatile("" ::: "memory");
; }
; template <bool NT> __device__ __forceinline__ void p0_items(Frame& F, int it0, int it1, int gw, int nw) {
;     LAS unsigned char* scr = F.lds + F.wave * 16384;
;     const int n4 = (F.lane & 15) * 4, kr = F.lane >> 4;
;     f32x4 va[16], vb[16]; P0Item A, B; int it = it0 + gw;
;     if (it < it1) { A = p0_decode(F, it, n4); p0_load(A, kr, va); }
;     while (it < it1) {
;         int itn = it + nw;
;         if (itn < it1) { B = p0_decode(F, itn, n4); p0_load(B, kr, vb); }
;         p0_finish<NT>(A, va, scr, F.lane);
;         it = itn; if (it >= it1) break;
;         itn = it + nw;
;         if (itn < it1) { A = p0_decode(F, itn, n4); p0_load(A, kr, va); }
;         p0_finish<NT>(B, vb, scr, F.lane);
;         it = itn;
	global_store_dwordx4 v[28:29], v[174:177], off
	v_lshlrev_b32_e32 v28, 2, v138
	v_and_b32_e32 v28, 16, v28
	v_lshrrev_b32_e32 v29, 1, v138
	v_and_or_b32 v173, v29, s21, v28
	v_ashrrev_i32_e32 v28, 3, v138
	v_and_b32_e32 v139, 3, v138
	v_and_b32_e32 v176, 0xffffffe0, v28
	v_and_or_b32 v139, v29, 12, v139
	v_add_u32_e32 v28, v176, v204
	v_ashrrev_i32_e32 v29, 31, v28
	v_lshlrev_b32_e32 v177, 5, v139
	v_and_b32_e32 v208, 16, v138
	v_lshrrev_b32_e32 v173, 3, v173
	v_bitop3_b32 v175, v177, v208, v206 bitop3:0x36
	v_lshlrev_b64 v[28:29], 15, v[28:29]
	v_lshlrev_b32_e32 v138, 9, v138
	v_or_b32_e32 v174, v173, v205
	v_lshl_add_u64 v[28:29], s[24:25], 0, v[28:29]
	v_and_b32_e32 v138, 0x4000, v138
	v_mov_b32_e32 v139, v26
	v_lshlrev_b32_e32 v175, 1, v175
	v_lshl_add_u64 v[28:29], v[28:29], 0, v[138:139]
	v_lshl_or_b32 v174, v174, 10, v175
	v_mov_b32_e32 v175, v26
	v_lshl_add_u64 v[28:29], v[28:29], 0, v[174:175]
	global_store_dwordx4 v[28:29], v[178:181], off
	v_add_u32_e32 v28, v176, v207
	v_ashrrev_i32_e32 v29, 31, v28
	v_lshlrev_b64 v[28:29], 15, v[28:29]
	v_bitop3_b32 v174, v177, v208, v27 bitop3:0x36
	v_lshl_add_u64 v[28:29], s[24:25], 0, v[28:29]
	v_or_b32_e32 v173, v173, v182
	v_lshl_add_u64 v[28:29], v[28:29], 0, v[138:139]
	v_lshlrev_b32_e32 v138, 1, v174
	v_lshl_or_b32 v138, v173, 10, v138
	v_lshl_add_u64 v[28:29], v[28:29], 0, v[138:139]
	v_add_u32_e32 v138, s17, v163
	s_waitcnt lgkmcnt(2)
	global_store_dwordx4 v[28:29], v[192:195], off
	v_lshlrev_b32_e32 v28, 2, v138
	v_and_b32_e32 v28, 16, v28
	v_lshrrev_b32_e32 v29, 1, v138
	v_and_or_b32 v173, v29, s21, v28
	v_ashrrev_i32_e32 v28, 3, v138
	v_and_b32_e32 v139, 3, v138
	v_and_b32_e32 v176, 0xffffffe0, v28
	v_and_or_b32 v139, v29, 12, v139
	v_add_u32_e32 v28, v176, v204
	v_ashrrev_i32_e32 v29, 31, v28
	v_lshlrev_b32_e32 v177, 5, v139
	v_and_b32_e32 v178, 16, v138
	v_lshrrev_b32_e32 v173, 3, v173
	v_bitop3_b32 v175, v177, v178, v206 bitop3:0x36
	v_lshlrev_b64 v[28:29], 15, v[28:29]
	v_lshlrev_b32_e32 v138, 9, v138
	v_or_b32_e32 v174, v173, v205
	v_lshl_add_u64 v[28:29], s[24:25], 0, v[28:29]
	v_and_b32_e32 v138, 0x4000, v138
	v_mov_b32_e32 v139, v26
	v_lshlrev_b32_e32 v175, 1, v175
	v_lshl_add_u64 v[28:29], v[28:29], 0, v[138:139]
	v_lshl_or_b32 v174, v174, 10, v175
	v_mov_b32_e32 v175, v26
	v_lshl_add_u64 v[28:29], v[28:29], 0, v[174:175]
	global_store_dwordx4 v[28:29], v[184:187], off
	v_add_u32_e32 v28, v176, v207
	v_ashrrev_i32_e32 v29, 31, v28
	v_lshlrev_b64 v[28:29], 15, v[28:29]
	v_bitop3_b32 v174, v177, v178, v27 bitop3:0x36
	v_lshl_add_u64 v[28:29], s[24:25], 0, v[28:29]
	v_or_b32_e32 v173, v173, v182
	v_lshl_add_u64 v[28:29], v[28:29], 0, v[138:139]
	v_lshlrev_b32_e32 v138, 1, v174
	v_lshl_or_b32 v138, v173, 10, v138
	v_lshl_add_u64 v[28:29], v[28:29], 0, v[138:139]
	v_add_u32_e32 v138, s17, v164
	s_waitcnt lgkmcnt(1)
	global_store_dwordx4 v[28:29], v[196:199], off
	v_lshlrev_b32_e32 v28, 2, v138
	v_and_b32_e32 v28, 16, v28
	v_lshrrev_b32_e32 v29, 1, v138
	v_and_or_b32 v173, v29, s21, v28
	v_ashrrev_i32_e32 v28, 3, v138
	v_and_b32_e32 v139, 3, v138
	v_and_b32_e32 v176, 0xffffffe0, v28
	v_and_or_b32 v139, v29, 12, v139
	v_add_u32_e32 v28, v176, v204
	v_ashrrev_i32_e32 v29, 31, v28
	v_lshlrev_b32_e32 v177, 5, v139
	v_and_b32_e32 v178, 16, v138
	v_lshrrev_b32_e32 v173, 3, v173
	v_bitop3_b32 v175, v177, v178, v206 bitop3:0x36
	v_lshlrev_b64 v[28:29], 15, v[28:29]
	v_lshlrev_b32_e32 v138, 9, v138
	v_or_b32_e32 v174, v173, v205
	v_lshl_add_u64 v[28:29], s[24:25], 0, v[28:29]
	v_and_b32_e32 v138, 0x4000, v138
	v_mov_b32_e32 v139, v26
	v_lshlrev_b32_e32 v175, 1, v175
	v_lshl_add_u64 v[28:29], v[28:29], 0, v[138:139]
	v_lshl_or_b32 v174, v174, 10, v175
	v_mov_b32_e32 v175, v26
	v_lshl_add_u64 v[28:29], v[28:29], 0, v[174:175]
	global_store_dwordx4 v[28:29], v[188:191], off
	v_add_u32_e32 v28, v176, v207
	v_ashrrev_i32_e32 v29, 31, v28
	v_bitop3_b32 v27, v177, v178, v27 bitop3:0x36
	v_lshlrev_b64 v[28:29], 15, v[28:29]
	v_or_b32_e32 v173, v173, v182
	v_lshl_add_u64 v[28:29], s[24:25], 0, v[28:29]
	v_lshlrev_b32_e32 v27, 1, v27
	v_lshl_add_u64 v[28:29], v[28:29], 0, v[138:139]
	v_lshl_or_b32 v138, v173, 10, v27
	v_lshl_add_u64 v[28:29], v[28:29], 0, v[138:139]
	s_waitcnt lgkmcnt(0)
	global_store_dwordx4 v[28:29], v[200:203], off
	s_waitcnt lgkmcnt(0)
	s_andn2_b64 vcc, exec, s[68:69]
	s_cbranch_vccnz .LBB0_56
	s_add_i32 s65, s65, s20
	s_cmpk_gt_i32 s65, 0x3247
	s_cbranch_scc1 .LBB0_145
	s_cmpk_gt_i32 s65, 0x18ff
	s_cbranch_scc0 .LBB0_107
	s_cmpk_gt_u32 s65, 0x1cff
	s_cbranch_scc0 .LBB0_108
	s_add_i32 s0, s65, 0xe300
	s_and_b32 s1, s0, 0xffff
	s_mul_i32 s1, s1, 0xba2f
	s_lshr_b32 s1, s1, 23
	s_mul_i32 s8, s1, 0xb0
	s_sub_i32 s0, s0, s8
	s_and_b32 s0, s0, 0xffff
	s_lshl_b32 s8, s0, 5
	s_lshl_b32 s17, s0, 6
	s_and_b32 s8, s8, 0x60
	s_lshl_b32 s0, s0, 7
	v_or_b32_e32 v4, s8, v142
	s_and_b32 s26, s0, 0x7e00
	v_lshl_add_u64 v[2:3], v[134:135], 0, s[26:27]
	v_lshlrev_b32_e32 v4, 2, v4
	v_mov_b32_e32 v5, v26
	v_lshl_add_u64 v[138:139], v[2:3], 0, v[4:5]
	s_lshl_b32 s63, s1, 6
	s_mov_b64 s[22:23], s[88:89]
	s_mov_b64 s[68:69], 0x1600
	s_mov_b64 s[24:25], s[4:5]
	s_cbranch_execz .LBB0_109
	s_branch .LBB0_110

;     __device__ __forceinline__ bf16* Win_t() const { return (bf16*)(ws + WS_WIN); }
;     __device__ __forceinline__ bf16* Wout_t() const { return (bf16*)(ws + WS_WOUT); }
;     __device__ __forceinline__ bf16* Wdown_t() const { return (bf16*)(ws + WS_WDOWN); }
;     __device__ __forceinline__ bf16* Wgu_t() const { return (bf16*)((unsigned char*)out + OUT_WGU); }
; __device__ __forceinline__ P0Item p0_decode(Frame& F, int it, int n4) {
;     ...
;     if (r < I_IN) { const int nblk = NP1 / 64, kb = r / nblk, nb = r % nblk, n = nb * 64 + n4;
;         const int sc = n < SRC_GLR ? n : n + GRANK;
;         q.srcp = F.w_in + sc; q.ldw = DIN; q.kscale = F.norm1_w; q.K = D; q.WT = F.Win_t(); q.n0 = nb * 64; q.k0 = kb * 64; return q; }
;     r -= I_IN;
;     if (r < I_OUT) { const int nblk = D / 64, kb = r / nblk, nb = r % nblk;
;         q.srcp = F.w_out + nb * 64 + n4; q.ldw = D; q.kscale = nullptr; q.K = D; q.WT = F.Wout_t(); q.n0 = nb * 64; q.k0 = kb * 64; return q; }
;     r -= I_OUT;
;     if (r < I_GU) { const int nblk = 2 * FF / 64, kb = r / nblk, nb = r % nblk, n0 = nb * 64, pn = n0 >> 8, wc = (n0 >> 6) & 3, bj = n4 >> 5, hl = 32 * wc + (n4 & 31);
;         q.srcp = (bj ? F.w_up : F.w_gate) + pn * 128 + hl; q.ldw = FF; q.kscale = F.norm2_w; q.K = D; q.WT = F.Wgu_t(); q.n0 = n0; q.k0 = kb * 64; return q; }
;     r -= I_GU;
;     { const int nblk = D / 64, kb = r / nblk, nb = r % nblk;
;         q.srcp = F.w_down + nb * 64 + n4; q.ldw = D; q.kscale = nullptr; q.K = FF; q.WT = F.Wdown_t(); q.n0 = nb * 64; q.k0 = kb * 64; return q; }
; __global__ void __launch_bounds__(NTHREADS, 2) hybrid_fwd(Args args) {
;     ...
;                 p1_glr(F, sw, nshort * NWAVES); p0_items<true>(F, P0_NITEMS - P0_DEFER_ITEMS, P0_NITEMS, sw, nshort * NWAVES); }
;             else if ((NT % F.G) == 0) { p1_glr(F, F.vcu * NWAVES + F.wave, F.G * NWAVES); p0_items<true>(F, P0_NITEMS - P0_DEFER_ITEMS, P0_NITEMS, F.vcu * NWAVES + F.wave, F.G * NWAVES); }
.LBB0_228:
	v_lshlrev_b32_e32 v20, 2, v183
	s_add_i32 s67, s0, 0x3248
	v_and_b32_e32 v142, 60, v20
	s_cmpk_gt_i32 s0, 0x11f7
	v_lshrrev_b32_e32 v143, 4, v183
	s_cbranch_scc1 .LBB0_233
	s_cmpk_gt_i32 s0, 0xecf7
	s_cbranch_scc0 .LBB0_234
	s_cmpk_gt_u32 s67, 0x1cff
	s_cbranch_scc0 .LBB0_235
	s_cmpk_gt_u32 s67, 0x32ff
	s_cbranch_scc0 .LBB0_236
	s_lshl_b32 s0, s67, 6
	s_and_b32 s64, s0, 0x7c0
	s_lshl_b32 s0, s64, 2
	s_add_u32 s0, s94, s0
	s_addc_u32 s1, s95, 0
	v_lshlrev_b32_e32 v2, 2, v142
	v_mov_b32_e32 v3, 0
	s_add_u32 s18, s56, 0x1200000
	v_lshl_add_u64 v[18:19], s[0:1], 0, v[2:3]
	s_addc_u32 s19, s57, 0
	s_lshl_b32 s0, s67, 1
	s_and_b32 s0, s0, 0x7fffffc0
	s_add_i32 s65, s0, 0xffff9a00
	s_mov_b64 s[20:21], 0
	s_mov_b64 s[6:7], 0
	s_branch .LBB0_237

;     __device__ __forceinline__ bf16* Win_t() const { return (bf16*)(ws + WS_WIN); }
;     __device__ __forceinline__ bf16* Wout_t() const { return (bf16*)(ws + WS_WOUT); }
;     __device__ __forceinline__ bf16* Wdown_t() const { return (bf16*)(ws + WS_WDOWN); }
;     __device__ __forceinline__ bf16* Wgu_t() const { return (bf16*)((unsigned char*)out + OUT_WGU); }
; __device__ __forceinline__ P0Item p0_decode(Frame& F, int it, int n4) {
;     ...
;     if (r < I_IN) { const int nblk = NP1 / 64, kb = r / nblk, nb = r % nblk, n = nb * 64 + n4;
;         const int sc = n < SRC_GLR ? n : n + GRANK;
;         q.srcp = F.w_in + sc; q.ldw = DIN; q.kscale = F.norm1_w; q.K = D; q.WT = F.Win_t(); q.n0 = nb * 64; q.k0 = kb * 64; return q; }
;     r -= I_IN;
;     if (r < I_OUT) { const int nblk = D / 64, kb = r / nblk, nb = r % nblk;
;         q.srcp = F.w_out + nb * 64 + n4; q.ldw = D; q.kscale = nullptr; q.K = D; q.WT = F.Wout_t(); q.n0 = nb * 64; q.k0 = kb * 64; return q; }
;     r -= I_OUT;
;     if (r < I_GU) { const int nblk = 2 * FF / 64, kb = r / nblk, nb = r % nblk, n0 = nb * 64, pn = n0 >> 8, wc = (n0 >> 6) & 3, bj = n4 >> 5, hl = 32 * wc + (n4 & 31);
;         q.srcp = (bj ? F.w_up : F.w_gate) + pn * 128 + hl; q.ldw = FF; q.kscale = F.norm2_w; q.K = D; q.WT = F.Wgu_t(); q.n0 = n0; q.k0 = kb * 64; return q; }
;     r -= I_GU;
;     { const int nblk = D / 64, kb = r / nblk, nb = r % nblk;
;         q.srcp = F.w_down + nb * 64 + n4; q.ldw = D; q.kscale = nullptr; q.K = FF; q.WT = F.Wdown_t(); q.n0 = nb * 64; q.k0 = kb * 64; return q; }
; __global__ void __launch_bounds__(NTHREADS, 2) hybrid_fwd(Args args) {
;     ...
;                 p1_glr(F, sw, nshort * NWAVES); p0_items<true>(F, P0_NITEMS - P0_DEFER_ITEMS, P0_NITEMS, sw, nshort * NWAVES); }
;             else if ((NT % F.G) == 0) { p1_glr(F, F.vcu * NWAVES + F.wave, F.G * NWAVES); p0_items<true>(F, P0_NITEMS - P0_DEFER_ITEMS, P0_NITEMS, F.vcu * NWAVES + F.wave, F.G * NWAVES); }
.LBB0_399:
	v_lshlrev_b32_e32 v20, 2, v183
	s_add_i32 s35, s0, 0x3248
	v_and_b32_e32 v142, 60, v20
	s_cmpk_gt_i32 s0, 0x11f7
	v_lshrrev_b32_e32 v143, 4, v183
	s_cbranch_scc1 .LBB0_421
	s_cmpk_gt_i32 s0, 0xecf7
	s_cbranch_scc0 .LBB0_439
	s_cmpk_gt_u32 s35, 0x1cff
	s_cbranch_scc0 .LBB0_912
	s_cmpk_gt_u32 s35, 0x32ff
	s_cbranch_scc0 .LBB0_913
	s_lshl_b32 s0, s35, 6
	s_and_b32 s36, s0, 0x7c0
	s_lshl_b32 s0, s36, 2
	s_add_u32 s0, s94, s0
	s_addc_u32 s1, s95, 0
	s_waitcnt vmcnt(0)
	v_lshlrev_b32_e32 v2, 2, v142
	v_mov_b32_e32 v3, 0
	s_add_u32 s6, s56, 0x1200000
	v_lshl_add_u64 v[18:19], s[0:1], 0, v[2:3]
	s_addc_u32 s7, s57, 0
	s_lshl_b32 s0, s35, 1
	s_and_b32 s0, s0, 0x7fffffc0
	s_add_i32 s37, s0, 0xffff9a00
	s_mov_b64 s[18:19], 0
	s_mov_b64 s[4:5], 0
	s_branch .LBB0_914
